# SCAN chunk top waits only for the prefetched loads (vmcnt(4): the 4 y stores stay in flight), full drain before the loop
# baseline (speedup 1.0000x reference)
; #define LAS __attribute__((address_space(3)))
; __device__ __forceinline__ void scan_prompt_unit(const Ctx& c, int b, int h) {
;     ...
;     f32x4 hacc[4];
; #pragma unroll
;     for (int pt = 0; pt < 4; ++pt) hacc[pt] = (f32x4){0.f, 0.f, 0.f, 0.f};
;     for (int i = tid; i < 64 * SROW / 4; i += 512) ((LAS unsigned*)(lds + SC_H))[i] = 0u;
;     u32x4 pc[4], pb[4], px[2]; float pdt[4], pac[4], pa_last, pa_mine = 0.f, pd_mine = 0.f;
;     const int prow = tid >> 4, pcc = tid & 15, xrow = tid >> 3, xcc = tid & 7;
;     ...
;     SCAN_LOAD(0);
;     __syncthreads();
.LBB0_146:
	s_or_b64 exec, exec, s[16:17]
	s_and_b32 s11, s96, 31
	s_lshl_b32 s12, s11, 2
	s_lshl_b32 s16, s11, 7
	s_lshl_b32 s11, s96, 5
	s_and_b32 s17, s11, 0x300
	s_add_u32 s12, s12, s14
	s_addc_u32 s13, 0, s15
	v_lshlrev_b64 v[0:1], 7, v[0:1]
	s_add_u32 s34, s12, 0x104bf80
	s_mul_hi_i32 s11, s10, 0x1800000
	s_mul_i32 s14, s10, 0x1800000
	v_lshl_add_u64 v[180:181], s[12:13], 0, v[0:1]
	s_addc_u32 s81, s13, 0
	s_or_b32 s10, s14, s16
	v_lshl_add_u64 v[184:185], s[12:13], 0, v[170:171]
	s_or_b32 s12, s14, s17
	s_mov_b32 s13, s11
	s_waitcnt vmcnt(19)
	v_mov_b32_e32 v179, v178
	v_lshl_add_u64 v[182:183], s[10:11], 0, v[168:169]
	v_lshl_add_u64 v[186:187], s[12:13], 0, v[172:173]
	v_lshl_add_u64 v[188:189], s[10:11], 0, v[174:175]
	s_mov_b32 s88, 32
	v_mov_b32_e32 v45, v44
	v_mov_b32_e32 v46, v44
	v_mov_b32_e32 v47, v44
	v_mov_b32_e32 v48, v44
	v_mov_b32_e32 v49, v44
	v_mov_b32_e32 v50, v44
	v_mov_b32_e32 v51, v44
	v_mov_b32_e32 v52, v44
	v_mov_b32_e32 v53, v44
	v_mov_b32_e32 v54, v44
	v_mov_b32_e32 v55, v44
	v_mov_b32_e32 v56, v44
	v_mov_b32_e32 v57, v44
	v_mov_b32_e32 v58, v44
	v_mov_b32_e32 v59, v44
	s_mov_b64 s[4:5], s[6:7]
	s_waitcnt vmcnt(0) lgkmcnt(0)
	s_barrier
	s_branch .LBB0_148

; __device__ __forceinline__ void scan_prompt_unit(const Ctx& c, int b, int h) {
;     ...
;     for (int ck = 0; ck < 32; ++ck) {
;         const size_t r0 = (size_t)b * PSEQ + (size_t)ck * 128;
;         asm volatile("s_waitcnt vmcnt(0)" : "+v"(pa_last), "+v"(pa_mine), "+v"(pd_mine), "+v"(pdt[0]), "+v"(pdt[1]), "+v"(pdt[2]), "+v"(pdt[3]), "+v"(pac[0]), "+v"(pac[1]), "+v"(pac[2]), "+v"(pac[3]) :: "memory");
;         asm volatile("" : "+v"(pc[0]), "+v"(pc[1]), "+v"(pc[2]), "+v"(pc[3]), "+v"(pb[0]), "+v"(pb[1]), "+v"(pb[2]), "+v"(pb[3]), "+v"(px[0]), "+v"(px[1]));
;         const float acs_last = pa_last;
;         if (tid < 128) { acsL[tid] = pa_mine; dtL[tid] = pd_mine; }
.LBB0_148:
	s_waitcnt vmcnt(4)
	v_mov_b32_e32 v0, v217
	s_waitcnt vmcnt(4)
	s_and_saveexec_b64 s[10:11], s[40:41]
	s_cbranch_execz .LBB0_150
	ds_write_b32 v190, v177
	ds_write_b32 v153, v214
